# grid barrier: the last XCD leader releases every XCD's local generation word directly (leaders no longer forward the release), on top of version 54
# speedup vs baseline: 1.0049x; 1.0017x over previous
.LBB0_128:
	s_or_b64 exec, exec, s[10:11]
	s_and_saveexec_b64 s[4:5], s[12:13]
	s_cbranch_execz .LBB0_130
	v_mov_b32_e32 v1, 1
	global_atomic_add v[2:3], v1, off
	v_readlane_b32 s100, v254, 6
	v_readlane_b32 s101, v254, 7
	s_nop 0
	s_add_u32 s98, s100, 0x3500
	v_cmp_eq_u32_e32 vcc, s98, v2
	s_add_u32 s100, s100, 0x2400
	s_addc_u32 s101, s101, 0
	s_and_saveexec_b64 s[98:99], vcc
	s_cbranch_execz .Lrelall_skip_0
	v_mov_b32_e32 v4, 0
	global_atomic_add v4, v1, s[100:101]
	global_atomic_add v4, v1, s[100:101] offset:256
	global_atomic_add v4, v1, s[100:101] offset:512
	global_atomic_add v4, v1, s[100:101] offset:768
	global_atomic_add v4, v1, s[100:101] offset:1024
	global_atomic_add v4, v1, s[100:101] offset:1280
	global_atomic_add v4, v1, s[100:101] offset:1536
	global_atomic_add v4, v1, s[100:101] offset:1792
	global_atomic_add v4, v1, s[100:101] offset:2048
	global_atomic_add v4, v1, s[100:101] offset:2304
	global_atomic_add v4, v1, s[100:101] offset:2560
	global_atomic_add v4, v1, s[100:101] offset:2816
	global_atomic_add v4, v1, s[100:101] offset:3072
	global_atomic_add v4, v1, s[100:101] offset:3328
	global_atomic_add v4, v1, s[100:101] offset:3584
	global_atomic_add v4, v1, s[100:101] offset:3840
.Lrelall_skip_0:
	s_or_b64 exec, exec, s[98:99]
.LBB0_130:
	s_or_b64 exec, exec, s[4:5]
	s_mov_b64 s[4:5], exec
	v_mbcnt_lo_u32_b32 v1, s4, 0
	v_mbcnt_hi_u32_b32 v1, s5, v1
	v_cmp_eq_u32_e32 vcc, 0, v1
	s_waitcnt vmcnt(0)
	s_and_saveexec_b64 s[8:9], vcc
	s_cbranch_execz .LBB0_132
	s_bcnt1_i32_b64 s4, s[4:5]
	v_mov_b32_e32 v1, 0
	v_mov_b32_e32 v2, s4
	s_nop 0

.LBB0_665:
	s_or_b64 exec, exec, s[8:9]
	s_and_saveexec_b64 s[2:3], s[10:11]
	s_cbranch_execz .LBB0_667
	v_mov_b32_e32 v1, 1
	global_atomic_add v[2:3], v1, off
	v_readlane_b32 s100, v254, 6
	v_readlane_b32 s101, v254, 7
	s_nop 0
	s_add_u32 s98, s100, 0x3500
	v_cmp_eq_u32_e32 vcc, s98, v2
	s_add_u32 s100, s100, 0x2400
	s_addc_u32 s101, s101, 0
	s_and_saveexec_b64 s[98:99], vcc
	s_cbranch_execz .Lrelall_skip_1
	v_mov_b32_e32 v4, 0
	global_atomic_add v4, v1, s[100:101]
	global_atomic_add v4, v1, s[100:101] offset:256
	global_atomic_add v4, v1, s[100:101] offset:512
	global_atomic_add v4, v1, s[100:101] offset:768
	global_atomic_add v4, v1, s[100:101] offset:1024
	global_atomic_add v4, v1, s[100:101] offset:1280
	global_atomic_add v4, v1, s[100:101] offset:1536
	global_atomic_add v4, v1, s[100:101] offset:1792
	global_atomic_add v4, v1, s[100:101] offset:2048
	global_atomic_add v4, v1, s[100:101] offset:2304
	global_atomic_add v4, v1, s[100:101] offset:2560
	global_atomic_add v4, v1, s[100:101] offset:2816
	global_atomic_add v4, v1, s[100:101] offset:3072
	global_atomic_add v4, v1, s[100:101] offset:3328
	global_atomic_add v4, v1, s[100:101] offset:3584
	global_atomic_add v4, v1, s[100:101] offset:3840

.LBB0_667:
	s_or_b64 exec, exec, s[2:3]
	s_mov_b64 s[2:3], exec
	v_mbcnt_lo_u32_b32 v1, s2, 0
	v_mbcnt_hi_u32_b32 v1, s3, v1
	v_cmp_eq_u32_e32 vcc, 0, v1
	s_waitcnt vmcnt(0)
	s_and_saveexec_b64 s[6:7], vcc
	s_cbranch_execz .LBB0_669
	s_bcnt1_i32_b64 s2, s[2:3]
	v_mov_b32_e32 v1, 0
	v_mov_b32_e32 v2, s2
	s_nop 0
